# v43 + GU GEMM column-tile order reversed (pn -> 43-pn) so the HID columns the down-projection reads first are the ones written last (memory-side cache reuse)
# speedup vs baseline: 1.0006x; 1.0001x over previous
; #define LAS __attribute__((address_space(3)))
; __device__ __forceinline__ unsigned xb_ld(unsigned* p)              { return __hip_atomic_load(p, __ATOMIC_RELAXED, __HIP_MEMORY_SCOPE_AGENT); }
; __device__ __forceinline__ void xcd_barrier_complete(unsigned* bar, unsigned x, unsigned& nloc, unsigned& nx) {
;     const unsigned G = gridDim.x * gridDim.y * gridDim.z;
;     unsigned sum, cnt, mine, sp = 0u;
;     for (;;) {
;         sum = 0u; cnt = 0u; mine = 0u;
; #pragma unroll
;         for (unsigned j = 0; j < 16; ++j) { const unsigned c = xb_ld(&bar[XB_XCNT(j)]); sum += c; cnt += (c > 0u) ? 1u : 0u; mine = (j == x) ? c : mine; }
;         if (sum == G) break;
;         __builtin_amdgcn_s_sleep(1);
;         if ((++sp & 255u) == 0u) { if (xb_ld(&bar[XB_TMO])) break; if (sp > XB_SPIN_CAP) { atomicAdd(&bar[XB_TMO], 1u); break; } }
;     }
;     nloc = mine > 0u ? mine : 1u; nx = cnt > 0u ? cnt : 1u;
; }
; __global__ void __launch_bounds__(NTHR) mega_fwd(Args a) {
;     ...
;     unsigned char* ws = a.ws;
;     const float* x_in = a.in[0]; const float* norm_g = a.in[1];
;     float* X = a.out;
;     bf16_t* W_GLA_IN = (bf16_t*)(ws + WS_GLA_IN); bf16_t* W_GLA_OUT = (bf16_t*)(ws + WS_GLA_OUT); bf16_t* W_POOL = (bf16_t*)(ws + WS_POOL);
;     bf16_t* W_DIFF_IN = (bf16_t*)(ws + WS_DIFF_IN); bf16_t* W_DIFF_OUT = (bf16_t*)(ws + WS_DIFF_OUT); bf16_t* W_GU = (bf16_t*)(ws + WS_GU); bf16_t* W_DOWN = (bf16_t*)(ws + WS_DOWN);
;     bf16_t* HN = (bf16_t*)(ws + WS_HN); bf16_t* PROJ = (bf16_t*)(ws + WS_PROJ); bf16_t* HID = (bf16_t*)(ws + WS_HID);
;     bf16_t* QT = (bf16_t*)(ws + WS_QT); bf16_t* KT = (bf16_t*)(ws + WS_KT); bf16_t* KH = (bf16_t*)(ws + WS_KH);
;     bf16_t* XB = (bf16_t*)(ws + WS_XB); float* DEC = (float*)(ws + WS_DEC); bf16_t* OI = (bf16_t*)(ws + WS_OI); bf16_t* OG = (bf16_t*)(ws + WS_OG);
;     const int lo = a.lo, hi = a.hi; int seam = 0; bool final_phase = false;
;     volatile LAS unsigned* MISC = (volatile LAS unsigned*)(lds + MISC_OFF);
;     if (threadIdx.x < 16) MISC[threadIdx.x] = 0u;
;     __syncthreads();
;     const XcdBarrier xbar = xcd_barrier_post((unsigned*)(ws + WS_BAR), MISC);
.LBB0_338:
	v_writelane_b32 v252, s68, 47
	s_lshl_b32 s0, s94, 9
	s_movk_i32 s25, 0xc1
	v_writelane_b32 v252, s69, 48
	s_add_u32 s68, s90, 0x16c00000
	s_addc_u32 s69, s91, 0
	s_add_u32 s56, s90, 0x1ac00000
	s_addc_u32 s57, s91, 0
	s_add_u32 s80, s90, 0x27400000
	s_addc_u32 s81, s91, 0
	s_add_u32 s82, s90, 0x32400000
	s_addc_u32 s83, s91, 0
	s_add_u32 s84, s90, 0x36400000
	s_addc_u32 s85, s91, 0
	s_add_u32 s86, s90, 0x44600000
	s_addc_u32 s87, s91, 0
	v_writelane_b32 v252, s0, 49
	s_add_u32 s0, s90, 0x38400000
	s_addc_u32 s1, s91, 0
	v_writelane_b32 v252, s0, 50
	v_lshrrev_b32_e32 v1, 20, v0
	v_lshrrev_b32_e32 v0, 10, v0
	v_writelane_b32 v252, s1, 51
	s_add_u32 s0, s90, 0x38500000
	s_addc_u32 s1, s91, 0
	s_add_u32 s14, s90, 0x40500000
	s_addc_u32 s15, s91, 0
	v_writelane_b32 v252, s0, 52
	s_cmpk_lt_i32 s2, 0x600
	s_cselect_b64 s[4:5], -1, 0
	v_writelane_b32 v252, s1, 53
	s_ashr_i32 s3, s2, 31
	v_writelane_b32 v252, s4, 54
	s_lshr_b32 s1, s3, 29
	s_mul_i32 s0, s95, s94
	v_writelane_b32 v252, s5, 55
	s_add_i32 s4, s2, s1
	s_ashr_i32 s1, s4, 3
	s_and_b32 s4, s4, -8
	s_sub_i32 s8, s2, s4
	s_ashr_i32 s95, s94, 31
	s_cmp_lt_i32 s92, 0
	s_cselect_b64 s[4:5], -1, 0
	v_writelane_b32 v252, s4, 56
	v_or_b32_e32 v0, v0, v1
	s_mul_i32 s10, s0, s10
	v_writelane_b32 v252, s5, 57
	s_add_u32 s4, s90, 0x44500200
	s_addc_u32 s5, s91, 0
	v_writelane_b32 v252, s4, 58
	v_mbcnt_lo_u32_b32 v2, -1, 0
	v_mov_b32_e32 v1, 0
	v_writelane_b32 v252, s5, 59
	s_add_u32 s4, s90, 0x44500400
	s_addc_u32 s5, s91, 0
	v_writelane_b32 v252, s4, 60
	v_mov_b32_e32 v187, 1
	v_mov_b32_e32 v189, 0x358637bd
	v_writelane_b32 v252, s5, 61
	s_add_u32 s4, s90, 0x44500500
	s_addc_u32 s5, s91, 0
	v_writelane_b32 v252, s4, 62
	v_mov_b32_e32 v191, 0x260
	v_mbcnt_hi_u32_b32 v193, -1, v2
	v_writelane_b32 v252, s5, 63
	s_add_u32 s4, s90, 0x44500600
	s_addc_u32 s5, s91, 0
	v_writelane_b32 v253, s4, 0
	v_mov_b32_e32 v195, 0x3000
	v_mov_b32_e32 v197, 0x41b17218
	v_writelane_b32 v253, s5, 1
	s_add_u32 s4, s90, 0x44500700
	s_addc_u32 s5, s91, 0
	v_writelane_b32 v253, s4, 2
	v_mov_b64_e32 v[166:167], 0x1ff
	s_mov_b32 s76, 1
	v_writelane_b32 v253, s5, 3
	s_add_u32 s4, s90, 0x44500800
	s_addc_u32 s5, s91, 0
	v_writelane_b32 v253, s4, 4
	s_movk_i32 s28, 0x3000
	s_mov_b32 s22, 0xf800000
	v_writelane_b32 v253, s5, 5
	s_add_u32 s4, s90, 0x44500900
	s_addc_u32 s5, s91, 0
	v_writelane_b32 v253, s4, 6
	s_mov_b32 s23, 0x3f317217
	s_mov_b32 s24, 0x7f800000
	v_writelane_b32 v253, s5, 7
	s_add_u32 s4, s90, 0x44500a00
	s_addc_u32 s5, s91, 0
	v_writelane_b32 v253, s4, 8
	s_mov_b32 s78, 0xff800000
	s_mov_b32 s26, 0xbfb8aa3b
	v_writelane_b32 v253, s5, 9
	s_add_u32 s4, s90, 0x44500b00
	s_addc_u32 s5, s91, 0
	v_writelane_b32 v253, s4, 10
	s_mov_b32 s27, 0x32420000
	s_movk_i32 s29, 0x2c00
	v_writelane_b32 v253, s5, 11
	s_add_u32 s4, s90, 0x44500c00
	s_addc_u32 s5, s91, 0
	v_writelane_b32 v253, s4, 12
	s_mov_b64 s[96:97], 0x1000
	s_mov_b64 s[58:59], 0x80000
	v_writelane_b32 v253, s5, 13
	s_add_u32 s4, s90, 0x44500d00
	s_addc_u32 s5, s91, 0
	v_writelane_b32 v253, s4, 14
	s_mov_b64 s[38:39], 0x80
	s_nop 0
	v_writelane_b32 v253, s5, 15
	s_add_u32 s4, s90, 0x44500e00
	s_addc_u32 s5, s91, 0
	v_writelane_b32 v253, s4, 16
	s_nop 1
	v_writelane_b32 v253, s5, 17
	s_add_u32 s4, s90, 0x44500f00
	s_addc_u32 s5, s91, 0
	v_writelane_b32 v253, s4, 18
	s_nop 1
	v_writelane_b32 v253, s5, 19
	s_add_u32 s4, s90, 0x44501000
	s_addc_u32 s5, s91, 0
	v_writelane_b32 v253, s4, 20
	s_nop 1
	v_writelane_b32 v253, s5, 21
	s_add_u32 s4, s90, 0x44501100
	s_addc_u32 s5, s91, 0
	v_writelane_b32 v253, s4, 22
	s_nop 1
	v_writelane_b32 v253, s5, 23
	s_add_u32 s4, s90, 0x44501200
	s_addc_u32 s5, s91, 0
	v_writelane_b32 v253, s4, 24
	s_nop 1
	v_writelane_b32 v253, s5, 25
	s_add_u32 s4, s90, 0x44501300
	s_addc_u32 s5, s91, 0
	v_writelane_b32 v253, s4, 26
	s_cmp_eq_u32 s11, 15
	s_nop 0
	v_writelane_b32 v253, s5, 27
	s_cselect_b64 s[4:5], -1, 0
	v_writelane_b32 v253, s4, 28
	s_cmp_eq_u32 s11, 14
	s_nop 0
	v_writelane_b32 v253, s5, 29
	s_cselect_b64 s[4:5], -1, 0
	v_writelane_b32 v253, s4, 30
	s_cmp_eq_u32 s11, 13
	s_nop 0
	v_writelane_b32 v253, s5, 31
	s_cselect_b64 s[4:5], -1, 0
	v_writelane_b32 v253, s4, 32
	s_cmp_eq_u32 s11, 12
	s_nop 0
	v_writelane_b32 v253, s5, 33
	s_cselect_b64 s[4:5], -1, 0
	v_writelane_b32 v253, s4, 34
	s_cmp_eq_u32 s11, 11
	s_nop 0
	v_writelane_b32 v253, s5, 35
	s_cselect_b64 s[4:5], -1, 0
	v_writelane_b32 v253, s4, 36
	s_cmp_eq_u32 s11, 10
	s_nop 0
	v_writelane_b32 v253, s5, 37
	s_cselect_b64 s[4:5], -1, 0
	v_writelane_b32 v253, s4, 38
	s_cmp_eq_u32 s11, 9
	s_nop 0
	v_writelane_b32 v253, s5, 39
	s_cselect_b64 s[4:5], -1, 0
	v_writelane_b32 v253, s4, 40
	s_cmp_eq_u32 s11, 8
	s_nop 0
	v_writelane_b32 v253, s5, 41
	s_cselect_b64 s[4:5], -1, 0
	v_writelane_b32 v253, s4, 42
	s_cmp_eq_u32 s11, 7
	s_nop 0
	v_writelane_b32 v253, s5, 43
	s_cselect_b64 s[4:5], -1, 0
	v_writelane_b32 v253, s4, 44
	s_cmp_eq_u32 s11, 6
	s_nop 0
	v_writelane_b32 v253, s5, 45
	s_cselect_b64 s[4:5], -1, 0
	v_writelane_b32 v253, s4, 46
	s_cmp_eq_u32 s11, 5
	s_nop 0
	v_writelane_b32 v253, s5, 47
	s_cselect_b64 s[4:5], -1, 0
	v_writelane_b32 v253, s4, 48
	s_cmp_eq_u32 s11, 4
	s_nop 0
	v_writelane_b32 v253, s5, 49
	s_cselect_b64 s[4:5], -1, 0
	v_writelane_b32 v253, s4, 50
	s_cmp_eq_u32 s11, 3
	s_nop 0
	v_writelane_b32 v253, s5, 51
	s_cselect_b64 s[4:5], -1, 0
	v_writelane_b32 v253, s4, 52
	s_cmp_eq_u32 s11, 2
	s_nop 0
	v_writelane_b32 v253, s5, 53
	s_cselect_b64 s[4:5], -1, 0
	v_writelane_b32 v253, s4, 54
	s_cmp_eq_u32 s11, 1
	s_nop 0
	v_writelane_b32 v253, s5, 55
	s_cselect_b64 s[4:5], -1, 0
	v_writelane_b32 v253, s4, 56
	s_cmp_eq_u32 s11, 0
	s_nop 0
; __device__ __forceinline__ unsigned xb_ld(unsigned* p)              { return __hip_atomic_load(p, __ATOMIC_RELAXED, __HIP_MEMORY_SCOPE_AGENT); }
; __device__ __forceinline__ unsigned xb_add(unsigned* p, unsigned v) { return __hip_atomic_fetch_add(p, v, __ATOMIC_RELAXED, __HIP_MEMORY_SCOPE_AGENT); }
; __device__ __forceinline__ void attn_phase(LAS unsigned char* lds, const bf16_t* proj, bf16_t* oa, const float* lamp, const float* subg, const float* relb, const float* qg, int wg, int tid) {
;     ...
;     const int xj = wg >> 3, bh = (wg & 7) * 4 + (xj >> 3), b = bh >> 3, h = bh & 7, sx = xj & 7;
;     const size_t rb = (size_t)b * SEQ;
;     const bf16_t* ksrc = proj + rb * DIFF_IN + 2048 + (2 * h) * 128;
;     const bf16_t* vsrc = proj + rb * DIFF_IN + 4096 + h * 256;
;     if (tid < 258) { const int sub = tid >= 129 ? 1 : 0, rel = tid - 129 * sub; int bucket;
;         if (rel < 16) bucket = rel; else if (rel >= 128) bucket = 31;
;         else { bucket = 16 + (int)(logf((float)rel / 16.0f) / 2.0794415416798357f * 16.0f); if (bucket > 31) bucket = 31; }
;         tb[sub * 132 + rel] = relb[bucket * 16 + 2 * h + sub] * LOG2E; }
;     const float c31a = relb[31 * 16 + 2 * h] * LOG2E, c31b = relb[31 * 16 + 2 * h + 1] * LOG2E;
;     for (int ui = 0; ui < 4; ++ui) {
;         const int qb = (ui == 0) ? sx : (ui == 1) ? 15 - sx : (ui == 2) ? 16 + sx : 31 - sx;
; __device__ __forceinline__ void xcd_barrier(const XcdBarrier& b) {
;     ...
;     if (threadIdx.x == 0) {
;         unsigned* bar = b.bar;
;         __builtin_amdgcn_s_waitcnt(0);
;         unsigned nloc = b.st[0], nx = b.st[1];
;         if (nloc == 0u) { xcd_barrier_complete(bar, b.x, nloc, nx); b.st[0] = nloc; b.st[1] = nx; }
;         const unsigned old = xb_add(&bar[XB_XSUB(b.x)], 1u);
;         const unsigned gen = old / nloc;
;         if (old + 1u == (gen + 1u) * nloc) {
;             __builtin_amdgcn_fence(__ATOMIC_RELEASE, "agent");
;             asm volatile("s_waitcnt vmcnt(0)" ::: "memory");
;             const unsigned og = xb_add(&bar[XB_TOP], 1u);
;             const unsigned tg = og / nx;
;             if (og + 1u == (tg + 1u) * nx) xb_add(&bar[XB_TOPGEN], 1u);
;             else XB_SPIN(xb_ld(&bar[XB_TOPGEN]) == tg, bar);
;             __builtin_amdgcn_fence(__ATOMIC_ACQUIRE, "agent");
;             xb_add(&bar[XB_XGEN(b.x)], 1u);
	v_writelane_b32 v253, s5, 57
	s_cselect_b64 s[4:5], -1, 0
	v_writelane_b32 v253, s4, 58
	s_nop 1
	v_writelane_b32 v253, s5, 59
	s_lshl_b32 s4, s11, 8
	s_add_u32 s4, s48, s4
	s_addc_u32 s5, s49, 0
	s_add_u32 s6, s4, 0x1400
	s_addc_u32 s7, s5, 0
	v_writelane_b32 v253, s6, 60
	s_add_u32 s4, s4, 0x2400
	s_addc_u32 s5, s5, 0
	v_writelane_b32 v253, s7, 61
	v_writelane_b32 v253, s4, 62
	s_nop 1
	v_writelane_b32 v253, s5, 63
	s_add_u32 s4, s90, 0x44503400
	s_addc_u32 s5, s91, 0
	v_writelane_b32 v254, s4, 0
	s_nop 1
	v_writelane_b32 v254, s5, 1
	s_add_u32 s4, s90, 0x44503500
	s_addc_u32 s5, s91, 0
	v_writelane_b32 v254, s4, 2
	s_lshl_b32 s11, s2, 9
	s_bfe_u32 s16, s2, 0x30003
	v_writelane_b32 v254, s5, 3
	s_lshl_b32 s4, s2, 2
	s_and_b32 s6, s4, 28
	s_ashr_i32 s5, s2, 6
	s_add_i32 s6, s6, s5
	s_ashr_i32 s12, s6, 3
	s_ashr_i32 s13, s12, 31
	s_and_b32 s9, s6, 7
	s_mul_hi_i32 s6, s12, 0x3000000
	s_mul_i32 s7, s12, 0x3000000
	s_lshl_b64 s[12:13], s[12:13], 12
	v_writelane_b32 v254, s12, 4
	s_nop 1
	v_writelane_b32 v254, s13, 5
	v_writelane_b32 v254, s11, 6
	s_lshl_b32 s11, s94, 5
	v_writelane_b32 v254, s11, 7
	s_add_u32 s11, s56, s7
	v_writelane_b32 v254, s16, 8
	s_addc_u32 s12, s57, s6
	s_lshl_b32 s13, s9, 1
	v_writelane_b32 v254, s13, 9
	s_lshl_b32 s13, s9, 9
	s_add_u32 s11, s11, s13
	s_addc_u32 s12, s12, 0
	s_add_u32 s18, s11, 0x1000
	s_addc_u32 s19, s12, 0
	v_writelane_b32 v254, s18, 10
	s_nop 1
	v_writelane_b32 v254, s19, 11
	s_add_u32 s18, s11, 0x2000
	s_addc_u32 s19, s12, 0
	v_writelane_b32 v254, s18, 12
	s_lshl_b32 s9, s9, 3
	s_mul_i32 s11, s8, 0x41
	v_writelane_b32 v254, s19, 13
	s_add_u32 s18, s66, s9
	s_addc_u32 s19, s67, 0
	v_writelane_b32 v254, s18, 14
	s_xor_b32 s9, s16, 15
	s_nop 0
	v_writelane_b32 v254, s19, 15
	v_writelane_b32 v254, s9, 16
	s_or_b32 s9, s16, 16
	v_writelane_b32 v254, s9, 17
	s_xor_b32 s9, s16, 31
	v_writelane_b32 v254, s9, 18
	s_add_u32 s16, s14, s13
	v_writelane_b32 v254, s14, 19
	s_addc_u32 s17, s15, 0
	s_add_u32 s12, s56, s13
	v_writelane_b32 v254, s15, 20
	v_writelane_b32 v254, s16, 21
	s_addc_u32 s13, s57, 0
	s_cmpk_lt_i32 s2, 0x100
	v_writelane_b32 v254, s17, 22
	v_writelane_b32 v254, s12, 23
	s_mov_b64 s[18:19], 0xb0000
	s_nop 0
	v_writelane_b32 v254, s13, 24
	s_cselect_b64 s[12:13], -1, 0
	v_writelane_b32 v254, s12, 25
	s_cmpk_lt_i32 s2, 0x400
	s_nop 0
	v_writelane_b32 v254, s13, 26
	s_cselect_b64 s[12:13], -1, 0
	v_writelane_b32 v254, s12, 27
	s_cmpk_lt_i32 s2, 0xb00
	s_nop 0
	v_writelane_b32 v254, s13, 28
	s_cselect_b64 s[12:13], -1, 0
	v_writelane_b32 v254, s12, 29
	s_cmpk_lt_i32 s2, 0x200
	s_nop 0
	v_writelane_b32 v254, s13, 30
	s_cselect_b64 s[12:13], -1, 0
	s_lshl_b32 s9, s8, 6
	s_cmp_lt_i32 s8, 0
	v_writelane_b32 v254, s12, 31
	s_cselect_b32 s11, s11, s9
	s_cselect_b32 s9, s25, 0xc0
	v_writelane_b32 v254, s13, 32
	s_mul_i32 s9, s8, s9
	s_movk_i32 s12, 0x161
	s_cselect_b32 s14, s12, 0x160
	s_add_i32 s9, s9, s1
	s_mul_hi_i32 s12, s9, 0x2aaaaaab
	s_lshr_b32 s13, s12, 31
	s_ashr_i32 s12, s12, 5
	s_add_i32 s12, s12, s13
	s_mul_i32 s13, s12, 0xc0
	s_sub_i32 s9, s9, s13
	s_bfe_u32 s13, s9, 0x3001c
	s_add_i32 s13, s9, s13
	s_and_b32 s15, s13, 0xfff8
	s_sub_i32 s9, s9, s15
	s_lshl_b32 s12, s12, 3
	s_sext_i32_i16 s13, s13
	s_sext_i32_i16 s9, s9
	s_add_i32 s16, s12, s9
	s_lshr_b32 s12, s13, 3
	s_ashr_i32 s9, s13, 3
	s_bfe_i64 s[12:13], s[12:13], 0x100000
	v_writelane_b32 v254, s9, 33
	s_lshl_b64 s[12:13], s[12:13], 20
	v_writelane_b32 v254, s12, 34
	s_ashr_i32 s17, s16, 31
	s_mul_i32 s8, s8, s14
	v_writelane_b32 v254, s13, 35
	s_mov_b32 s12, s16
	v_writelane_b32 v254, s12, 36
	s_nop 1
	v_writelane_b32 v254, s13, 37
	s_lshl_b64 s[12:13], s[16:17], 20
	s_add_u32 s12, s68, s12
	s_addc_u32 s13, s69, s13
	s_add_u32 s14, s12, 0x80000
	v_writelane_b32 v254, s12, 38
	s_addc_u32 s15, s13, 0
	s_add_i32 s8, s8, s1
	s_mul_hi_i32 s9, s8, 0x2e8ba2e9
	v_writelane_b32 v254, s13, 39
	s_lshr_b32 s12, s9, 31
	s_ashr_i32 s9, s9, 6
	s_add_i32 s9, s9, s12
	s_mul_i32 s12, s9, 0x160
	s_sub_i32 s8, s8, s12
	s_bfe_u32 s12, s8, 0x3001c
;     __host__ __device__ bool next(int i, Unit& u) const {
;         const long L = (long)i * G + c; if (L >= nwg) return false;
;         int wgid = (int)L; { const int q = nwg / NXCD, r = nwg % NXCD, xcd = wgid % NXCD, off = wgid / NXCD; wgid = (xcd < r ? xcd * (q + 1) : r * (q + 1) + (xcd - r) * q) + off; }
;         const int nig = wgm * nN, gid = wgid / nig, fm = gid * wgm, gsz = (nM - fm) < wgm ? (nM - fm) : wgm;
;         u.pm = fm + ((wgid % nig) % gsz); u.pn = (wgid % nig) / gsz; return true;
	s_add_i32 s12, s8, s12
	s_and_b32 s13, s12, 0xfff8
	s_sub_i32 s8, s8, s13
	v_writelane_b32 v254, s14, 40
	s_lshl_b32 s9, s9, 3
	s_sext_i32_i16 s12, s12
	s_sext_i32_i16 s8, s8
	v_writelane_b32 v254, s15, 41
	s_add_i32 s14, s9, s8
	s_ashr_i32 s8, s12, 3
	s_sub_i32 s8, 43, s8
	v_writelane_b32 v254, s8, 42
	s_lshr_b32 s8, s12, 3
	s_sub_i32 s8, 43, s8
	s_bfe_i64 s[8:9], s[8:9], 0x100000
	s_lshl_b64 s[8:9], s[8:9], 20
	v_writelane_b32 v254, s8, 43
	s_ashr_i32 s15, s14, 31
	s_mov_b64 s[16:17], 0xa0000
	v_writelane_b32 v254, s9, 44
	s_mov_b32 s8, s14
	v_writelane_b32 v254, s8, 45
	s_nop 1
	v_writelane_b32 v254, s9, 46
	s_lshl_b64 s[8:9], s[14:15], 20
	s_add_u32 s12, s68, s8
	s_addc_u32 s13, s69, s9
	s_movk_i32 s8, 0x3ff
	v_and_or_b32 v0, v0, s8, v175
	s_add_u32 s8, s12, 0x80000
	v_writelane_b32 v254, s12, 47
	s_addc_u32 s9, s13, 0
	s_add_i32 s0, s11, s1
	s_ashr_i32 s1, s0, 31
	v_writelane_b32 v254, s13, 48
	s_lshr_b32 s1, s1, 27
	v_writelane_b32 v254, s8, 49
	s_add_i32 s1, s0, s1
	s_mov_b32 s11, 0x800000
	v_writelane_b32 v254, s9, 50
	s_and_b32 s8, s1, 0xffe0
	s_sub_i32 s0, s0, s8
	s_bfe_i32 s8, s0, 0x80000
	s_bfe_u32 s8, s8, 0x2000d
	s_add_i32 s8, s0, s8
	s_and_b32 s9, s8, 0xfc
	s_sub_i32 s0, s0, s9
	s_ashr_i32 s1, s1, 5
	s_lshl_b32 s1, s1, 2
	s_sext_i32_i8 s0, s0
	s_add_i32 s9, s1, s0
	s_bfe_i32 s0, s8, 0x80000
	s_sext_i32_i16 s8, s0
	s_ashr_i32 s0, s8, 3
	s_ashr_i32 s1, s0, 31
	s_lshl_b64 s[0:1], s[0:1], 10
	v_writelane_b32 v254, s0, 51
	s_mov_b64 s[14:15], 0x90000
	s_nop 0
	v_writelane_b32 v254, s1, 52
	s_ashr_i32 s1, s8, 2
	s_lshr_b32 s0, s8, 2
	s_bfe_i64 s[12:13], s[0:1], 0x100000
	v_writelane_b32 v254, s12, 53
	s_lshl_b32 s0, s9, 8
	s_nop 0
	v_writelane_b32 v254, s13, 54
	v_writelane_b32 v254, s9, 55
	v_writelane_b32 v254, s0, 56
	v_writelane_b32 v254, s1, 57
	s_lshl_b32 s0, s1, 8
	v_writelane_b32 v254, s0, 58
	s_add_u32 s0, s90, 0x4050f000
	s_addc_u32 s1, s91, 0
	v_writelane_b32 v254, s0, 59
	s_add_i32 s4, s4, s5
	s_mov_b64 s[8:9], 0x60000
	v_writelane_b32 v254, s1, 60
	s_and_b32 s0, s4, 7
	s_lshl_b32 s1, s2, 10
	v_writelane_b32 v254, s1, 61
	s_lshl_b32 s1, s94, 10
	s_lshl_b32 s72, s0, 9
	s_add_u32 s0, s90, s7
	v_writelane_b32 v254, s1, 62
	s_addc_u32 s1, s91, s6
	s_add_u32 s4, s0, 0x1ac62000
	s_addc_u32 s5, s1, 0
	s_add_u32 s0, s0, 0x1ac61000
	v_writelane_b32 v254, s4, 63
	s_addc_u32 s1, s1, 0
	s_mov_b32 s7, 0
	v_writelane_b32 v255, s5, 0
	v_writelane_b32 v255, s0, 1
	s_mov_b32 s73, s7
	s_mov_b32 s6, 0
	v_writelane_b32 v255, s1, 2
	s_add_u32 s0, s90, 0x1800100
	v_writelane_b32 v255, s0, 3
	s_addc_u32 s0, s91, 0
	v_writelane_b32 v255, s0, 4
	s_lshl_b64 s[0:1], s[2:3], 18
	s_add_u32 s0, s90, s0
	s_addc_u32 s1, s91, s1
	s_add_u32 s0, s0, 0x16c00100
	v_writelane_b32 v255, s0, 5
	s_addc_u32 s0, s1, 0
	v_writelane_b32 v255, s0, 6
	s_lshl_b32 s0, s2, 1
	v_writelane_b32 v255, s0, 7
	s_lshl_b32 s0, s94, 1
	v_writelane_b32 v255, s0, 8
	s_add_i32 s0, 0, 0x25400
	v_writelane_b32 v255, s0, 9
	s_add_i32 s0, 0, 0x25404
	v_writelane_b32 v255, s0, 10
	s_add_i32 s0, 0, 0x11800
	v_writelane_b32 v255, s0, 11
	s_add_i32 s0, 0, 0x12800
	v_writelane_b32 v255, s0, 12
	s_add_i32 s0, 0, 0x11000
	v_writelane_b32 v255, s0, 13
	s_add_i32 s0, 0, 0x1b400
	v_writelane_b32 v255, s0, 14
	s_add_i32 s0, 0, 0x12c00
	v_writelane_b32 v255, s0, 15
	s_add_i32 s0, 0, 0x13800
	v_writelane_b32 v255, s0, 16
	s_add_i32 s0, 0, 0x24000
	v_writelane_b32 v255, s0, 17
	v_cmp_eq_u32_e64 s[0:1], 0, v0
	s_ashr_i32 s71, s70, 31
	s_lshl_b64 s[4:5], s[70:71], 12
	v_writelane_b32 v255, s0, 18
	s_mov_b32 s71, s10
	s_mov_b32 s10, 0x3d800000
	v_writelane_b32 v255, s1, 19
	s_lshl_b64 s[0:1], s[94:95], 18
	v_writelane_b32 v255, s0, 20
	s_mov_b64 s[12:13], 0x20000
	s_nop 0
	v_writelane_b32 v255, s1, 21
	s_mov_b64 s[0:1], 0
	v_writelane_b32 v255, s0, 22
	s_nop 1
	v_writelane_b32 v255, s1, 23
	s_mov_b32 s0, s70
	v_writelane_b32 v255, s0, 24
	s_nop 1
	v_writelane_b32 v255, s1, 25
	v_writelane_b32 v255, s56, 26
	s_nop 1
	v_writelane_b32 v255, s57, 27
	v_writelane_b32 v255, s71, 28
	s_branch .LBB0_341

;     __host__ __device__ bool next(int i, Unit& u) const {
;         const long L = (long)i * G + c; if (L >= nwg) return false;
;         int wgid = (int)L; { const int q = nwg / NXCD, r = nwg % NXCD, xcd = wgid % NXCD, off = wgid / NXCD; wgid = (xcd < r ? xcd * (q + 1) : r * (q + 1) + (xcd - r) * q) + off; }
;         const int nig = wgm * nN, gid = wgid / nig, fm = gid * wgm, gsz = (nM - fm) < wgm ? (nM - fm) : wgm;
;         u.pm = fm + ((wgid % nig) % gsz); u.pn = (wgid % nig) / gsz; return true;
.LBB0_1086:
	s_add_i32 s70, s70, 1
	s_mul_i32 s30, s70, s95
	s_mul_hi_u32 s31, s70, s94
	s_add_i32 s31, s31, s30
	s_mul_i32 s30, s70, s94
	s_add_u32 s44, s30, s2
	s_addc_u32 s45, s31, s3
	v_mov_b64_e32 v[2:3], 0xb00
	v_cmp_lt_i64_e64 s[40:41], s[44:45], v[2:3]
	v_mov_b64_e32 v[2:3], 0xaff
	v_cmp_gt_i64_e32 vcc, s[44:45], v[2:3]
	s_cbranch_vccnz .LBB0_1088
	s_ashr_i32 s30, s44, 31
	s_lshr_b32 s30, s30, 29
	s_add_i32 s30, s44, s30
	s_ashr_i32 s31, s30, 3
	s_and_b32 s30, s30, -8
	s_sub_i32 s30, s44, s30
	s_cmp_lt_i32 s30, 0
	s_movk_i32 s25, 0x161
	s_cselect_b32 s42, s25, 0x160
	s_mul_i32 s30, s30, s42
	s_add_i32 s30, s30, s31
	s_mul_hi_i32 s31, s30, 0x2e8ba2e9
	s_lshr_b32 s42, s31, 31
	s_ashr_i32 s31, s31, 6
	s_add_i32 s31, s31, s42
	s_lshl_b32 s42, s31, 3
	s_sub_i32 s43, 64, s42
	s_min_i32 s43, s43, 8
	s_abs_i32 s44, s43
	v_cvt_f32_u32_e32 v2, s44
	s_sub_i32 s49, 0, s44
	s_mulk_i32 s31, 0x160
	s_sub_i32 s30, s30, s31
	v_rcp_iflag_f32_e32 v2, v2
	s_abs_i32 s31, s30
	s_xor_b32 s45, s30, s43
	s_ashr_i32 s45, s45, 31
	v_mul_f32_e32 v2, 0x4f7ffffe, v2
	v_cvt_u32_f32_e32 v2, v2
	s_nop 0
	v_readfirstlane_b32 s50, v2
	s_mul_i32 s49, s49, s50
	s_mul_hi_u32 s49, s50, s49
	s_add_i32 s50, s50, s49
	s_mul_hi_u32 s49, s31, s50
	s_mul_i32 s50, s49, s44
	s_sub_i32 s31, s31, s50
	s_add_i32 s51, s49, 1
	s_sub_i32 s50, s31, s44
	s_cmp_ge_u32 s31, s44
	s_cselect_b32 s49, s51, s49
	s_cselect_b32 s31, s50, s31
	s_add_i32 s50, s49, 1
	s_cmp_ge_u32 s31, s44
	s_cselect_b32 s31, s50, s49
	s_xor_b32 s31, s31, s45
	s_sub_i32 s66, s31, s45
	s_mul_i32 s31, s66, s43
	s_sub_i32 s30, s30, s31
	s_add_i32 s42, s42, s30
	s_sub_i32 s66, 43, s66
